# nt (streaming) hint on the FFN-up SwiGLU output stores
# speedup vs baseline: 1.0098x; 1.0098x over previous
; __device__ __forceinline__ unsigned pk2(float lo, float hi) { f32x2_t v = {lo, hi}; bf16x2_t b = __builtin_convertvector(v, bf16x2_t); return __builtin_bit_cast(unsigned, b); }
; __device__ __forceinline__ float siluf_(float x) { return x * sigmoidf_(x); }
; #define RSTD_GET(ai, m) __int_as_float(__builtin_amdgcn_ds_bpermute(((m) * 16 + fr) << 2, __float_as_int((ai) ? es1 : es0)))
; __device__ __forceinline__ float row_rstd(const float* SS, int row) {
;     const f32x4* p = (const f32x4*)(SS + (size_t)row * 32);
;     float s = 0.f;
; #pragma unroll
;     for (int j = 0; j < 8; ++j) { const f32x4 a = p[j]; s += (a[0] + a[1]) + (a[2] + a[3]); }
;     return rsqrtf(s * (1.f / 1024.f) + EPS);
;     __device__ __forceinline__ void operator()(EPI_ARGS) const {
; #pragma unroll
;         for (int ai = 0; ai < 2; ++ai) {
;             if (ai == 1 && u.half) break;
; #pragma unroll
;             for (int m = 0; m < 4; ++m) {
;                 int row = EPI_ROWS(ai, m); asm volatile("" : "+v"(row)); const float rs = RSTD_GET(ai, m);
;                 float o[8];
; #pragma unroll
;                 for (int n = 0; n < 2; ++n)
; #pragma unroll
;                     for (int e = 0; e < 4; ++e) { const float g = acc[ai][0][m][n][e] * rs, up = acc[ai][1][m][n][e] * rs; o[n * 4 + e] = siluf_(g) * up; }
;                 u32x4 w; w.x = pk2(o[0], o[1]); w.y = pk2(o[2], o[3]); w.z = pk2(o[4], o[5]); w.w = pk2(o[6], o[7]);
;                 *(u32x4*)(T + (size_t)row * FF + u.pn * 128 + wc * 32 + 8 * fq) = w;
.LBB0_899:
	s_lshl_b32 s2, s63, 8
	v_mov_b32_e32 v247, 0
	v_add3_u32 v246, s2, v143, v142
	s_mov_b64 s[2:3], 0x4000
	v_lshlrev_b64 v[246:247], 7, v[246:247]
	v_lshl_add_u64 v[246:247], s[94:95], 0, v[246:247]
	v_lshl_add_u64 v[244:245], v[246:247], 0, s[2:3]
	global_load_dwordx4 v[204:207], v[246:247], off
	global_load_dwordx4 v[208:211], v[246:247], off offset:16
	global_load_dwordx4 v[212:215], v[246:247], off offset:32
	global_load_dwordx4 v[216:219], v[246:247], off offset:48
	global_load_dwordx4 v[220:223], v[246:247], off offset:64
	global_load_dwordx4 v[224:227], v[246:247], off offset:80
	global_load_dwordx4 v[228:231], v[246:247], off offset:96
	global_load_dwordx4 v[232:235], v[246:247], off offset:112
	global_load_dwordx4 v[236:239], v[244:245], off
	global_load_dwordx4 v[240:243], v[244:245], off offset:16
	global_load_dwordx4 v[180:183], v[244:245], off offset:32
	global_load_dwordx4 v[184:187], v[244:245], off offset:48
	global_load_dwordx4 v[190:193], v[244:245], off offset:64
	global_load_dwordx4 v[194:197], v[244:245], off offset:80
	global_load_dwordx4 v[160:163], v[244:245], off offset:96
	global_load_dwordx4 v[244:247], v[244:245], off offset:112
	s_lshl_b32 s26, s26, 8
	v_readlane_b32 s2, v255, 10
	v_readlane_b32 s3, v255, 11
	s_andn2_b64 vcc, exec, s[36:37]
	ds_bpermute_b32 v159, v145, v141
	v_add_u32_e32 v158, s26, v144
	s_nop 0
	v_mov_b64_e32 v[156:157], s[2:3]
	s_nop 0
	v_mad_i64_i32 v[154:155], s[38:39], v158, s71, v[156:157]
	s_lshl_b32 s2, s27, 7
	s_ashr_i32 s3, s2, 31
	s_lshl_b64 s[2:3], s[2:3], 1
	v_lshl_add_u64 v[154:155], v[154:155], 0, s[2:3]
	v_lshl_add_u64 v[154:155], v[154:155], 0, s[4:5]
	v_lshl_add_u64 v[154:155], v[154:155], 0, v[168:169]
	s_mov_b64 s[38:39], 0x16000
	s_waitcnt lgkmcnt(0)
	v_mul_f32_e32 v156, 0xbfb8aa3b, v159
	v_mul_f32_e32 v158, v159, v159
	ds_bpermute_b32 v159, v148, v141
	v_pk_mul_f32 v[120:121], v[120:121], v[124:125]
	v_pk_mul_f32 v[122:123], v[122:123], v[126:127]
	v_pk_mul_f32 v[112:113], v[112:113], v[116:117]
	v_pk_mul_f32 v[114:115], v[114:115], v[118:119]
	v_pk_mul_f32 v[124:125], v[124:125], v[156:157] op_sel_hi:[1,0]
	v_pk_mul_f32 v[126:127], v[126:127], v[156:157] op_sel_hi:[1,0]
	v_pk_mul_f32 v[116:117], v[116:117], v[156:157] op_sel_hi:[1,0]
	v_pk_mul_f32 v[118:119], v[118:119], v[156:157] op_sel_hi:[1,0]
	v_exp_f32_e32 v124, v124
	v_exp_f32_e32 v125, v125
	v_exp_f32_e32 v126, v126
	v_exp_f32_e32 v127, v127
	v_exp_f32_e32 v116, v116
	v_exp_f32_e32 v117, v117
	v_exp_f32_e32 v118, v118
	v_exp_f32_e32 v119, v119
	v_pk_add_f32 v[124:125], v[124:125], 1.0 op_sel_hi:[1,0]
	v_pk_add_f32 v[126:127], v[126:127], 1.0 op_sel_hi:[1,0]
	v_pk_add_f32 v[116:117], v[116:117], 1.0 op_sel_hi:[1,0]
	v_pk_add_f32 v[118:119], v[118:119], 1.0 op_sel_hi:[1,0]
	v_rcp_f32_e32 v124, v124
	v_rcp_f32_e32 v125, v125
	v_rcp_f32_e32 v126, v126
	v_rcp_f32_e32 v127, v127
	v_rcp_f32_e32 v116, v116
	v_rcp_f32_e32 v117, v117
	v_rcp_f32_e32 v118, v118
	v_rcp_f32_e32 v119, v119
	v_pk_mul_f32 v[120:121], v[120:121], v[158:159] op_sel_hi:[1,0]
	v_pk_mul_f32 v[122:123], v[122:123], v[158:159] op_sel_hi:[1,0]
	v_pk_mul_f32 v[112:113], v[112:113], v[158:159] op_sel_hi:[1,0]
	v_pk_mul_f32 v[114:115], v[114:115], v[158:159] op_sel_hi:[1,0]
	v_pk_mul_f32 v[120:121], v[120:121], v[124:125]
	v_pk_mul_f32 v[122:123], v[122:123], v[126:127]
	v_pk_mul_f32 v[112:113], v[112:113], v[116:117]
	v_pk_mul_f32 v[114:115], v[114:115], v[118:119]
	v_cvt_pk_bf16_f32 v124, v120, v121
	v_cvt_pk_bf16_f32 v125, v122, v123
	v_cvt_pk_bf16_f32 v126, v112, v113
	v_cvt_pk_bf16_f32 v127, v114, v115
	global_store_dwordx4 v[154:155], v[124:127], off nt
	v_lshl_add_u64 v[154:155], v[154:155], 0, s[38:39]
	s_waitcnt lgkmcnt(0)
	v_mul_f32_e32 v156, 0xbfb8aa3b, v159
	v_mul_f32_e32 v158, v159, v159
	ds_bpermute_b32 v159, v150, v141
	v_pk_mul_f32 v[104:105], v[104:105], v[108:109]
	v_pk_mul_f32 v[106:107], v[106:107], v[110:111]
	v_pk_mul_f32 v[96:97], v[96:97], v[100:101]
	v_pk_mul_f32 v[98:99], v[98:99], v[102:103]
	v_pk_mul_f32 v[108:109], v[108:109], v[156:157] op_sel_hi:[1,0]
	v_pk_mul_f32 v[110:111], v[110:111], v[156:157] op_sel_hi:[1,0]
	v_pk_mul_f32 v[100:101], v[100:101], v[156:157] op_sel_hi:[1,0]
	v_pk_mul_f32 v[102:103], v[102:103], v[156:157] op_sel_hi:[1,0]
	v_exp_f32_e32 v108, v108
	v_exp_f32_e32 v109, v109
	v_exp_f32_e32 v110, v110
	v_exp_f32_e32 v111, v111
	v_exp_f32_e32 v100, v100
	v_exp_f32_e32 v101, v101
	v_exp_f32_e32 v102, v102
	v_exp_f32_e32 v103, v103
	v_pk_add_f32 v[108:109], v[108:109], 1.0 op_sel_hi:[1,0]
	v_pk_add_f32 v[110:111], v[110:111], 1.0 op_sel_hi:[1,0]
	v_pk_add_f32 v[100:101], v[100:101], 1.0 op_sel_hi:[1,0]
	v_pk_add_f32 v[102:103], v[102:103], 1.0 op_sel_hi:[1,0]
	v_rcp_f32_e32 v108, v108
	v_rcp_f32_e32 v109, v109
	v_rcp_f32_e32 v110, v110
	v_rcp_f32_e32 v111, v111
	v_rcp_f32_e32 v100, v100
	v_rcp_f32_e32 v101, v101
	v_rcp_f32_e32 v102, v102
	v_rcp_f32_e32 v103, v103
	v_pk_mul_f32 v[104:105], v[104:105], v[158:159] op_sel_hi:[1,0]
	v_pk_mul_f32 v[106:107], v[106:107], v[158:159] op_sel_hi:[1,0]
	v_pk_mul_f32 v[96:97], v[96:97], v[158:159] op_sel_hi:[1,0]
	v_pk_mul_f32 v[98:99], v[98:99], v[158:159] op_sel_hi:[1,0]
	v_pk_mul_f32 v[104:105], v[104:105], v[108:109]
	v_pk_mul_f32 v[106:107], v[106:107], v[110:111]
	v_pk_mul_f32 v[96:97], v[96:97], v[100:101]
	v_pk_mul_f32 v[98:99], v[98:99], v[102:103]
	v_cvt_pk_bf16_f32 v108, v104, v105
	v_cvt_pk_bf16_f32 v109, v106, v107
	v_cvt_pk_bf16_f32 v110, v96, v97
	v_cvt_pk_bf16_f32 v111, v98, v99
	global_store_dwordx4 v[154:155], v[108:111], off nt
	v_lshl_add_u64 v[154:155], v[154:155], 0, s[38:39]
	s_waitcnt lgkmcnt(0)
; __device__ __forceinline__ unsigned pk2(float lo, float hi) { f32x2_t v = {lo, hi}; bf16x2_t b = __builtin_convertvector(v, bf16x2_t); return __builtin_bit_cast(unsigned, b); }
; __device__ __forceinline__ float siluf_(float x) { return x * sigmoidf_(x); }
; #define RSTD_GET(ai, m) __int_as_float(__builtin_amdgcn_ds_bpermute(((m) * 16 + fr) << 2, __float_as_int((ai) ? es1 : es0)))
;     __device__ __forceinline__ void operator()(EPI_ARGS) const {
;     ...
;             for (int m = 0; m < 4; ++m) {
;                 int row = EPI_ROWS(ai, m); asm volatile("" : "+v"(row)); const float rs = RSTD_GET(ai, m);
;                 float o[8];
; #pragma unroll
;                 for (int n = 0; n < 2; ++n)
; #pragma unroll
;                     for (int e = 0; e < 4; ++e) { const float g = acc[ai][0][m][n][e] * rs, up = acc[ai][1][m][n][e] * rs; o[n * 4 + e] = siluf_(g) * up; }
;                 u32x4 w; w.x = pk2(o[0], o[1]); w.y = pk2(o[2], o[3]); w.z = pk2(o[4], o[5]); w.w = pk2(o[6], o[7]);
;                 *(u32x4*)(T + (size_t)row * FF + u.pn * 128 + wc * 32 + 8 * fq) = w;
	v_mul_f32_e32 v156, 0xbfb8aa3b, v159
	v_mul_f32_e32 v158, v159, v159
	ds_bpermute_b32 v159, v152, v141
	v_pk_mul_f32 v[88:89], v[88:89], v[92:93]
	v_pk_mul_f32 v[90:91], v[90:91], v[94:95]
	v_pk_mul_f32 v[80:81], v[80:81], v[84:85]
	v_pk_mul_f32 v[82:83], v[82:83], v[86:87]
	v_pk_mul_f32 v[92:93], v[92:93], v[156:157] op_sel_hi:[1,0]
	v_pk_mul_f32 v[94:95], v[94:95], v[156:157] op_sel_hi:[1,0]
	v_pk_mul_f32 v[84:85], v[84:85], v[156:157] op_sel_hi:[1,0]
	v_pk_mul_f32 v[86:87], v[86:87], v[156:157] op_sel_hi:[1,0]
	v_exp_f32_e32 v92, v92
	v_exp_f32_e32 v93, v93
	v_exp_f32_e32 v94, v94
	v_exp_f32_e32 v95, v95
	v_exp_f32_e32 v84, v84
	v_exp_f32_e32 v85, v85
	v_exp_f32_e32 v86, v86
	v_exp_f32_e32 v87, v87
	v_pk_add_f32 v[92:93], v[92:93], 1.0 op_sel_hi:[1,0]
	v_pk_add_f32 v[94:95], v[94:95], 1.0 op_sel_hi:[1,0]
	v_pk_add_f32 v[84:85], v[84:85], 1.0 op_sel_hi:[1,0]
	v_pk_add_f32 v[86:87], v[86:87], 1.0 op_sel_hi:[1,0]
	v_rcp_f32_e32 v92, v92
	v_rcp_f32_e32 v93, v93
	v_rcp_f32_e32 v94, v94
	v_rcp_f32_e32 v95, v95
	v_rcp_f32_e32 v84, v84
	v_rcp_f32_e32 v85, v85
	v_rcp_f32_e32 v86, v86
	v_rcp_f32_e32 v87, v87
	v_pk_mul_f32 v[88:89], v[88:89], v[158:159] op_sel_hi:[1,0]
	v_pk_mul_f32 v[90:91], v[90:91], v[158:159] op_sel_hi:[1,0]
	v_pk_mul_f32 v[80:81], v[80:81], v[158:159] op_sel_hi:[1,0]
	v_pk_mul_f32 v[82:83], v[82:83], v[158:159] op_sel_hi:[1,0]
	v_pk_mul_f32 v[88:89], v[88:89], v[92:93]
	v_pk_mul_f32 v[90:91], v[90:91], v[94:95]
	v_pk_mul_f32 v[80:81], v[80:81], v[84:85]
	v_pk_mul_f32 v[82:83], v[82:83], v[86:87]
	v_cvt_pk_bf16_f32 v92, v88, v89
	v_cvt_pk_bf16_f32 v93, v90, v91
	v_cvt_pk_bf16_f32 v94, v80, v81
	v_cvt_pk_bf16_f32 v95, v82, v83
	global_store_dwordx4 v[154:155], v[92:95], off nt
	v_lshl_add_u64 v[154:155], v[154:155], 0, s[38:39]
	s_waitcnt lgkmcnt(0)
	v_mul_f32_e32 v156, 0xbfb8aa3b, v159
	v_mul_f32_e32 v158, v159, v159
	ds_bpermute_b32 v159, v145, v140
	v_pk_mul_f32 v[72:73], v[72:73], v[76:77]
	v_pk_mul_f32 v[74:75], v[74:75], v[78:79]
	v_pk_mul_f32 v[64:65], v[64:65], v[68:69]
	v_pk_mul_f32 v[66:67], v[66:67], v[70:71]
	v_pk_mul_f32 v[76:77], v[76:77], v[156:157] op_sel_hi:[1,0]
	v_pk_mul_f32 v[78:79], v[78:79], v[156:157] op_sel_hi:[1,0]
	v_pk_mul_f32 v[68:69], v[68:69], v[156:157] op_sel_hi:[1,0]
	v_pk_mul_f32 v[70:71], v[70:71], v[156:157] op_sel_hi:[1,0]
	v_exp_f32_e32 v76, v76
	v_exp_f32_e32 v77, v77
	v_exp_f32_e32 v78, v78
	v_exp_f32_e32 v79, v79
	v_exp_f32_e32 v68, v68
	v_exp_f32_e32 v69, v69
	v_exp_f32_e32 v70, v70
	v_exp_f32_e32 v71, v71
	v_pk_add_f32 v[76:77], v[76:77], 1.0 op_sel_hi:[1,0]
	v_pk_add_f32 v[78:79], v[78:79], 1.0 op_sel_hi:[1,0]
	v_pk_add_f32 v[68:69], v[68:69], 1.0 op_sel_hi:[1,0]
	v_pk_add_f32 v[70:71], v[70:71], 1.0 op_sel_hi:[1,0]
	v_rcp_f32_e32 v76, v76
	v_rcp_f32_e32 v77, v77
	v_rcp_f32_e32 v78, v78
	v_rcp_f32_e32 v79, v79
	v_rcp_f32_e32 v68, v68
	v_rcp_f32_e32 v69, v69
	v_rcp_f32_e32 v70, v70
	v_rcp_f32_e32 v71, v71
	v_pk_mul_f32 v[72:73], v[72:73], v[158:159] op_sel_hi:[1,0]
	v_pk_mul_f32 v[74:75], v[74:75], v[158:159] op_sel_hi:[1,0]
	v_pk_mul_f32 v[64:65], v[64:65], v[158:159] op_sel_hi:[1,0]
	v_pk_mul_f32 v[66:67], v[66:67], v[158:159] op_sel_hi:[1,0]
	v_pk_mul_f32 v[72:73], v[72:73], v[76:77]
	v_pk_mul_f32 v[74:75], v[74:75], v[78:79]
	v_pk_mul_f32 v[64:65], v[64:65], v[68:69]
	v_pk_mul_f32 v[66:67], v[66:67], v[70:71]
	v_cvt_pk_bf16_f32 v76, v72, v73
	v_cvt_pk_bf16_f32 v77, v74, v75
	v_cvt_pk_bf16_f32 v78, v64, v65
	v_cvt_pk_bf16_f32 v79, v66, v67
	s_mov_b64 s[38:39], 0x6e000
	global_store_dwordx4 v[154:155], v[76:79], off nt
	v_lshl_add_u64 v[154:155], v[154:155], 0, s[38:39]
	s_mov_b64 s[38:39], 0x16000
	s_waitcnt lgkmcnt(0)
	v_mul_f32_e32 v156, 0xbfb8aa3b, v159
	v_mul_f32_e32 v158, v159, v159
	ds_bpermute_b32 v159, v148, v140
	v_pk_mul_f32 v[56:57], v[56:57], v[60:61]
	v_pk_mul_f32 v[58:59], v[58:59], v[62:63]
	v_pk_mul_f32 v[48:49], v[48:49], v[52:53]
	v_pk_mul_f32 v[50:51], v[50:51], v[54:55]
	v_pk_mul_f32 v[60:61], v[60:61], v[156:157] op_sel_hi:[1,0]
	v_pk_mul_f32 v[62:63], v[62:63], v[156:157] op_sel_hi:[1,0]
	v_pk_mul_f32 v[52:53], v[52:53], v[156:157] op_sel_hi:[1,0]
	v_pk_mul_f32 v[54:55], v[54:55], v[156:157] op_sel_hi:[1,0]
	v_exp_f32_e32 v60, v60
	v_exp_f32_e32 v61, v61
	v_exp_f32_e32 v62, v62
	v_exp_f32_e32 v63, v63
	v_exp_f32_e32 v52, v52
	v_exp_f32_e32 v53, v53
	v_exp_f32_e32 v54, v54
	v_exp_f32_e32 v55, v55
	v_pk_add_f32 v[60:61], v[60:61], 1.0 op_sel_hi:[1,0]
	v_pk_add_f32 v[62:63], v[62:63], 1.0 op_sel_hi:[1,0]
	v_pk_add_f32 v[52:53], v[52:53], 1.0 op_sel_hi:[1,0]
	v_pk_add_f32 v[54:55], v[54:55], 1.0 op_sel_hi:[1,0]
	v_rcp_f32_e32 v60, v60
	v_rcp_f32_e32 v61, v61
	v_rcp_f32_e32 v62, v62
	v_rcp_f32_e32 v63, v63
	v_rcp_f32_e32 v52, v52
	v_rcp_f32_e32 v53, v53
	v_rcp_f32_e32 v54, v54
	v_rcp_f32_e32 v55, v55
	v_pk_mul_f32 v[56:57], v[56:57], v[158:159] op_sel_hi:[1,0]
	v_pk_mul_f32 v[58:59], v[58:59], v[158:159] op_sel_hi:[1,0]
	v_pk_mul_f32 v[48:49], v[48:49], v[158:159] op_sel_hi:[1,0]
	v_pk_mul_f32 v[50:51], v[50:51], v[158:159] op_sel_hi:[1,0]
	v_pk_mul_f32 v[56:57], v[56:57], v[60:61]
	v_pk_mul_f32 v[58:59], v[58:59], v[62:63]
	v_pk_mul_f32 v[48:49], v[48:49], v[52:53]
	v_pk_mul_f32 v[50:51], v[50:51], v[54:55]
	v_cvt_pk_bf16_f32 v60, v56, v57
	v_cvt_pk_bf16_f32 v61, v58, v59
	v_cvt_pk_bf16_f32 v62, v48, v49
	v_cvt_pk_bf16_f32 v63, v50, v51
	global_store_dwordx4 v[154:155], v[60:63], off nt
	v_lshl_add_u64 v[154:155], v[154:155], 0, s[38:39]
	s_waitcnt lgkmcnt(0)
; __device__ __forceinline__ unsigned pk2(float lo, float hi) { f32x2_t v = {lo, hi}; bf16x2_t b = __builtin_convertvector(v, bf16x2_t); return __builtin_bit_cast(unsigned, b); }
; __device__ __forceinline__ float siluf_(float x) { return x * sigmoidf_(x); }
; #define RSTD_GET(ai, m) __int_as_float(__builtin_amdgcn_ds_bpermute(((m) * 16 + fr) << 2, __float_as_int((ai) ? es1 : es0)))
; template <class Epi, class Sched>
; __device__ __forceinline__ void gemm_phase(const int tid, LAS unsigned char* lds, const int lda, const int ldb, const int K, const Sched& S, const Epi& E) {
;     ...
;         if (!has_next) break;
;     __device__ __forceinline__ void operator()(EPI_ARGS) const {
;     ...
;             for (int m = 0; m < 4; ++m) {
;                 int row = EPI_ROWS(ai, m); asm volatile("" : "+v"(row)); const float rs = RSTD_GET(ai, m);
;                 float o[8];
; #pragma unroll
;                 for (int n = 0; n < 2; ++n)
; #pragma unroll
;                     for (int e = 0; e < 4; ++e) { const float g = acc[ai][0][m][n][e] * rs, up = acc[ai][1][m][n][e] * rs; o[n * 4 + e] = siluf_(g) * up; }
;                 u32x4 w; w.x = pk2(o[0], o[1]); w.y = pk2(o[2], o[3]); w.z = pk2(o[4], o[5]); w.w = pk2(o[6], o[7]);
;                 *(u32x4*)(T + (size_t)row * FF + u.pn * 128 + wc * 32 + 8 * fq) = w;
	v_mul_f32_e32 v156, 0xbfb8aa3b, v159
	v_mul_f32_e32 v158, v159, v159
	ds_bpermute_b32 v159, v150, v140
	v_pk_mul_f32 v[40:41], v[40:41], v[44:45]
	v_pk_mul_f32 v[42:43], v[42:43], v[46:47]
	v_pk_mul_f32 v[32:33], v[32:33], v[36:37]
	v_pk_mul_f32 v[34:35], v[34:35], v[38:39]
	v_pk_mul_f32 v[44:45], v[44:45], v[156:157] op_sel_hi:[1,0]
	v_pk_mul_f32 v[46:47], v[46:47], v[156:157] op_sel_hi:[1,0]
	v_pk_mul_f32 v[36:37], v[36:37], v[156:157] op_sel_hi:[1,0]
	v_pk_mul_f32 v[38:39], v[38:39], v[156:157] op_sel_hi:[1,0]
	v_exp_f32_e32 v44, v44
	v_exp_f32_e32 v45, v45
	v_exp_f32_e32 v46, v46
	v_exp_f32_e32 v47, v47
	v_exp_f32_e32 v36, v36
	v_exp_f32_e32 v37, v37
	v_exp_f32_e32 v38, v38
	v_exp_f32_e32 v39, v39
	v_pk_add_f32 v[44:45], v[44:45], 1.0 op_sel_hi:[1,0]
	v_pk_add_f32 v[46:47], v[46:47], 1.0 op_sel_hi:[1,0]
	v_pk_add_f32 v[36:37], v[36:37], 1.0 op_sel_hi:[1,0]
	v_pk_add_f32 v[38:39], v[38:39], 1.0 op_sel_hi:[1,0]
	v_rcp_f32_e32 v44, v44
	v_rcp_f32_e32 v45, v45
	v_rcp_f32_e32 v46, v46
	v_rcp_f32_e32 v47, v47
	v_rcp_f32_e32 v36, v36
	v_rcp_f32_e32 v37, v37
	v_rcp_f32_e32 v38, v38
	v_rcp_f32_e32 v39, v39
	v_pk_mul_f32 v[40:41], v[40:41], v[158:159] op_sel_hi:[1,0]
	v_pk_mul_f32 v[42:43], v[42:43], v[158:159] op_sel_hi:[1,0]
	v_pk_mul_f32 v[32:33], v[32:33], v[158:159] op_sel_hi:[1,0]
	v_pk_mul_f32 v[34:35], v[34:35], v[158:159] op_sel_hi:[1,0]
	v_pk_mul_f32 v[40:41], v[40:41], v[44:45]
	v_pk_mul_f32 v[42:43], v[42:43], v[46:47]
	v_pk_mul_f32 v[32:33], v[32:33], v[36:37]
	v_pk_mul_f32 v[34:35], v[34:35], v[38:39]
	v_cvt_pk_bf16_f32 v44, v40, v41
	v_cvt_pk_bf16_f32 v45, v42, v43
	v_cvt_pk_bf16_f32 v46, v32, v33
	v_cvt_pk_bf16_f32 v47, v34, v35
	global_store_dwordx4 v[154:155], v[44:47], off nt
	v_lshl_add_u64 v[154:155], v[154:155], 0, s[38:39]
	s_waitcnt lgkmcnt(0)
	v_mul_f32_e32 v156, 0xbfb8aa3b, v159
	v_mul_f32_e32 v158, v159, v159
	ds_bpermute_b32 v159, v152, v140
	v_pk_mul_f32 v[24:25], v[24:25], v[28:29]
	v_pk_mul_f32 v[26:27], v[26:27], v[30:31]
	v_pk_mul_f32 v[16:17], v[16:17], v[20:21]
	v_pk_mul_f32 v[18:19], v[18:19], v[22:23]
	v_pk_mul_f32 v[28:29], v[28:29], v[156:157] op_sel_hi:[1,0]
	v_pk_mul_f32 v[30:31], v[30:31], v[156:157] op_sel_hi:[1,0]
	v_pk_mul_f32 v[20:21], v[20:21], v[156:157] op_sel_hi:[1,0]
	v_pk_mul_f32 v[22:23], v[22:23], v[156:157] op_sel_hi:[1,0]
	v_exp_f32_e32 v28, v28
	v_exp_f32_e32 v29, v29
	v_exp_f32_e32 v30, v30
	v_exp_f32_e32 v31, v31
	v_exp_f32_e32 v20, v20
	v_exp_f32_e32 v21, v21
	v_exp_f32_e32 v22, v22
	v_exp_f32_e32 v23, v23
	v_pk_add_f32 v[28:29], v[28:29], 1.0 op_sel_hi:[1,0]
	v_pk_add_f32 v[30:31], v[30:31], 1.0 op_sel_hi:[1,0]
	v_pk_add_f32 v[20:21], v[20:21], 1.0 op_sel_hi:[1,0]
	v_pk_add_f32 v[22:23], v[22:23], 1.0 op_sel_hi:[1,0]
	v_rcp_f32_e32 v28, v28
	v_rcp_f32_e32 v29, v29
	v_rcp_f32_e32 v30, v30
	v_rcp_f32_e32 v31, v31
	v_rcp_f32_e32 v20, v20
	v_rcp_f32_e32 v21, v21
	v_rcp_f32_e32 v22, v22
	v_rcp_f32_e32 v23, v23
	v_pk_mul_f32 v[24:25], v[24:25], v[158:159] op_sel_hi:[1,0]
	v_pk_mul_f32 v[26:27], v[26:27], v[158:159] op_sel_hi:[1,0]
	v_pk_mul_f32 v[16:17], v[16:17], v[158:159] op_sel_hi:[1,0]
	v_pk_mul_f32 v[18:19], v[18:19], v[158:159] op_sel_hi:[1,0]
	v_pk_mul_f32 v[24:25], v[24:25], v[28:29]
	v_pk_mul_f32 v[26:27], v[26:27], v[30:31]
	v_pk_mul_f32 v[16:17], v[16:17], v[20:21]
	v_pk_mul_f32 v[18:19], v[18:19], v[22:23]
	v_cvt_pk_bf16_f32 v28, v24, v25
	v_cvt_pk_bf16_f32 v29, v26, v27
	v_cvt_pk_bf16_f32 v30, v16, v17
	v_cvt_pk_bf16_f32 v31, v18, v19
	global_store_dwordx4 v[154:155], v[28:31], off nt
	v_lshl_add_u64 v[154:155], v[154:155], 0, s[38:39]
	s_waitcnt lgkmcnt(0)
	v_mul_f32_e32 v156, 0xbfb8aa3b, v159
	v_mul_f32_e32 v158, v159, v159
	v_pk_mul_f32 v[8:9], v[8:9], v[12:13]
	v_pk_mul_f32 v[10:11], v[10:11], v[14:15]
	v_pk_mul_f32 v[0:1], v[0:1], v[4:5]
	v_pk_mul_f32 v[2:3], v[2:3], v[6:7]
	v_pk_mul_f32 v[12:13], v[12:13], v[156:157] op_sel_hi:[1,0]
	v_pk_mul_f32 v[14:15], v[14:15], v[156:157] op_sel_hi:[1,0]
	v_pk_mul_f32 v[4:5], v[4:5], v[156:157] op_sel_hi:[1,0]
	v_pk_mul_f32 v[6:7], v[6:7], v[156:157] op_sel_hi:[1,0]
	v_exp_f32_e32 v12, v12
	v_exp_f32_e32 v13, v13
	v_exp_f32_e32 v14, v14
	v_exp_f32_e32 v15, v15
	v_exp_f32_e32 v4, v4
	v_exp_f32_e32 v5, v5
	v_exp_f32_e32 v6, v6
	v_exp_f32_e32 v7, v7
	v_pk_add_f32 v[12:13], v[12:13], 1.0 op_sel_hi:[1,0]
	v_pk_add_f32 v[14:15], v[14:15], 1.0 op_sel_hi:[1,0]
	v_pk_add_f32 v[4:5], v[4:5], 1.0 op_sel_hi:[1,0]
	v_pk_add_f32 v[6:7], v[6:7], 1.0 op_sel_hi:[1,0]
	v_rcp_f32_e32 v12, v12
	v_rcp_f32_e32 v13, v13
	v_rcp_f32_e32 v14, v14
	v_rcp_f32_e32 v15, v15
	v_rcp_f32_e32 v4, v4
	v_rcp_f32_e32 v5, v5
	v_rcp_f32_e32 v6, v6
	v_rcp_f32_e32 v7, v7
	v_pk_mul_f32 v[8:9], v[8:9], v[158:159] op_sel_hi:[1,0]
	v_pk_mul_f32 v[10:11], v[10:11], v[158:159] op_sel_hi:[1,0]
	v_pk_mul_f32 v[0:1], v[0:1], v[158:159] op_sel_hi:[1,0]
	v_pk_mul_f32 v[2:3], v[2:3], v[158:159] op_sel_hi:[1,0]
	v_pk_mul_f32 v[8:9], v[8:9], v[12:13]
	v_pk_mul_f32 v[10:11], v[10:11], v[14:15]
	v_pk_mul_f32 v[0:1], v[0:1], v[4:5]
	v_pk_mul_f32 v[2:3], v[2:3], v[6:7]
	v_cvt_pk_bf16_f32 v12, v8, v9
	v_cvt_pk_bf16_f32 v13, v10, v11
	v_cvt_pk_bf16_f32 v14, v0, v1
	v_cvt_pk_bf16_f32 v15, v2, v3
	s_mov_b64 s[2:3], -1
	global_store_dwordx4 v[154:155], v[12:15], off nt
	s_cbranch_vccnz .LBB0_891
; #define PG8_BAR __builtin_amdgcn_s_barrier()
; template <class Epi, class Sched>
; __device__ __forceinline__ void gemm_phase(const int tid, LAS unsigned char* lds, const int lda, const int ldb, const int K, const Sched& S, const Epi& E) {
;     ...
;         E.pre(nxt, wr, wc, fr, fq, es0, es1);
;         E.init(acc, nxt, wr, wc, fr, fq);
;         cur = nxt; cA = nA; cB = nB; ++ui;
;         if (wr == 1) PG8_BAR;
; __device__ __forceinline__ float row_rstd(const float* SS, int row) {
;     const f32x4* p = (const f32x4*)(SS + (size_t)row * 32);
;     float s = 0.f;
; #pragma unroll
;     for (int j = 0; j < 8; ++j) { const f32x4 a = p[j]; s += (a[0] + a[1]) + (a[2] + a[3]); }
;     return rsqrtf(s * (1.f / 1024.f) + EPS);
	s_waitcnt vmcnt(8)
	v_add_f32_e32 v4, v204, v205
	v_add_f32_e32 v6, v236, v237
	v_add_f32_e32 v5, v206, v207
	v_add_f32_e32 v7, v238, v239
	v_add_f32_e32 v1, v4, v5
	v_add_f32_e32 v0, v6, v7
	v_add_f32_e32 v1, 0, v1
	v_add_f32_e32 v0, 0, v0
	v_add_f32_e32 v4, v208, v209
	v_add_f32_e32 v6, v240, v241
	v_add_f32_e32 v5, v210, v211
	v_add_f32_e32 v7, v242, v243
	v_add_f32_e32 v4, v4, v5
	v_add_f32_e32 v6, v6, v7
	v_add_f32_e32 v1, v1, v4
	v_add_f32_e32 v0, v0, v6
	v_add_f32_e32 v4, v212, v213
	v_add_f32_e32 v6, v180, v181
	v_add_f32_e32 v5, v214, v215
	v_add_f32_e32 v7, v182, v183
	v_add_f32_e32 v4, v4, v5
	v_add_f32_e32 v6, v6, v7
	v_add_f32_e32 v1, v1, v4
	v_add_f32_e32 v0, v0, v6
	v_add_f32_e32 v4, v216, v217
	v_add_f32_e32 v6, v184, v185
	v_add_f32_e32 v5, v218, v219
	v_add_f32_e32 v7, v186, v187
	v_add_f32_e32 v4, v4, v5
	v_add_f32_e32 v6, v6, v7
	v_add_f32_e32 v1, v1, v4
	v_add_f32_e32 v0, v0, v6
	v_add_f32_e32 v4, v220, v221
	v_add_f32_e32 v6, v190, v191
	v_add_f32_e32 v5, v222, v223
	v_add_f32_e32 v7, v192, v193
	v_add_f32_e32 v4, v4, v5
	v_add_f32_e32 v6, v6, v7
	v_add_f32_e32 v1, v1, v4
	v_add_f32_e32 v0, v0, v6
	v_add_f32_e32 v4, v224, v225
	v_add_f32_e32 v6, v194, v195
	v_add_f32_e32 v5, v226, v227
	v_add_f32_e32 v7, v196, v197
	v_add_f32_e32 v4, v4, v5
	v_add_f32_e32 v6, v6, v7
	v_add_f32_e32 v1, v1, v4
	v_add_f32_e32 v0, v0, v6
	v_add_f32_e32 v4, v228, v229
	v_add_f32_e32 v6, v160, v161
	v_add_f32_e32 v5, v230, v231
	v_add_f32_e32 v7, v162, v163
	v_add_f32_e32 v4, v4, v5
	v_add_f32_e32 v6, v6, v7
	v_add_f32_e32 v1, v1, v4
	v_add_f32_e32 v0, v0, v6
	v_add_f32_e32 v4, v232, v233
	v_add_f32_e32 v6, v244, v245
	v_add_f32_e32 v5, v234, v235
	v_add_f32_e32 v7, v246, v247
	v_add_f32_e32 v4, v4, v5
	v_add_f32_e32 v6, v6, v7
	v_add_f32_e32 v1, v1, v4
	v_add_f32_e32 v0, v0, v6
	s_mov_b32 s2, 0x3a800000
	s_andn2_b64 vcc, exec, s[22:23]
	s_nop 0
	v_pk_fma_f32 v[0:1], v[0:1], s[2:3], v[170:171] op_sel_hi:[1,0,0]
	s_nop 0
	v_cmp_gt_f32_e64 s[36:37], s33, v0
	v_cmp_gt_f32_e64 s[38:39], s33, v1
	s_cbranch_vccnz .LBB0_890
	s_barrier
	s_branch .LBB0_890
